# rmsnorm row-scale table of RETIN/UG phases: all units partial-sum loads issued first, one wait, then reduce
# speedup vs baseline: 1.0579x; 1.0005x over previous
; #define LAS __attribute__((address_space(3)))
;     __host__ __device__ __forceinline__ bool next(int i, Unit& u) const {
;         const long L = (long)i * G + c; if (L >= nwg) return false;
;         int wgid = (int)L; { const int q = nwg / NXCD, r = nwg % NXCD, xcd = wgid % NXCD, off = wgid / NXCD; wgid = (xcd < r ? xcd * (q + 1) : r * (q + 1) + (xcd - r) * q) + off; }
;         const int nig = WGM * nN, gid = wgid / nig, fm = gid * WGM, gsz = (nM - fm) < WGM ? (nM - fm) : WGM;
;         u.pm = fm + ((wgid % nig) % gsz); u.pn = (wgid % nig) / gsz; u.ord = i; return true;
; __global__ void __launch_bounds__(NTHR, 2) mega(Params p, int lo, int hi) {
;     ...
;             pg8::StaticOrder S; S.init(gM, gN, (int)gridDim.x, (int)blockIdx.x);
;             if (E.kind == EK_RETIN || E.kind == EK_UG) {
;                 LAS float* rt = (LAS float*)(lds + 131072);
;                 Unit uu;
;                 for (int ui = 0; ui < 8 && S.next(ui, uu); ++ui) if (tid < 256) { int rr = ug ? 254 * uu.pm - 2 + tid : uu.pm * 256 + tid; rr = rr < 0 ? 0 : (rr > M - 1 ? M - 1 : rr); rt[ui * 256 + tid] = row_rstd(ws, E.slot, rr); }
.LBB0_470:
	s_and_b64 vcc, exec, s[44:45]
	v_readlane_b32 s27, v255, 20
	s_cbranch_vccz .LBB0_1410
	s_xor_b64 s[8:9], s[72:73], -1
	s_or_b64 s[0:1], s[72:73], s[2:3]
	s_and_b64 s[0:1], s[0:1], exec
	s_movk_i32 s0, 0x42
	s_cselect_b32 s4, s0, 0x41
	s_and_b64 s[0:1], s[60:61], exec
	s_waitcnt lgkmcnt(0)
	s_load_dword s80, s[88:89], 0x0
	s_cselect_b32 s0, 64, s4
	v_writelane_b32 v255, s0, 32
	s_mov_b32 s1, 0
	s_mul_i32 s24, s50, s0
	s_and_b32 s0, s51, 5
	v_writelane_b32 v255, s1, 34
	s_cmp_lg_u32 s0, 0
	v_readlane_b32 s27, v255, 20
	s_cbranch_scc1 .LBB0_579
	s_mov_b32 s101, 0
	s_lshr_b32 s19, s24, 3
	s_and_b32 s20, s24, 6
	s_add_i32 s18, s19, 1
	s_lshl_b32 s13, s50, 2
	s_cmp_lt_i32 s92, s24
	s_mul_i32 s21, s18, s20
	s_cselect_b64 s[0:1], -1, 0
	s_cmp_ge_i32 s92, s24
	v_readlane_b32 s27, v255, 20
	s_cbranch_scc1 .LBB0_478
	v_readlane_b32 s4, v252, 27
	s_cmp_ge_i32 s4, s20
	s_mov_b64 s[4:5], -1
	s_cbranch_scc0 .LBB0_475
	v_readlane_b32 s4, v252, 27
	s_sub_i32 s4, s4, s20
	s_mul_i32 s4, s4, s19
	s_add_i32 s6, s4, s21
	s_mov_b64 s[4:5], 0

; __device__ __forceinline__ float row_rstd(const unsigned char* ws, int slot, int row) {
;     const f32x4* q = (const f32x4*)((const float*)(ws + WS_SS) + ((size_t)slot * M + row) * 16);
;     const f32x4 a = q[0], b = q[1], c = q[2], d = q[3];
; __global__ void __launch_bounds__(NTHR, 2) mega(Params p, int lo, int hi) {
;     ...
;                 Unit uu;
;                 for (int ui = 0; ui < 8 && S.next(ui, uu); ++ui) if (tid < 256) { int rr = ug ? 254 * uu.pm - 2 + tid : uu.pm * 256 + tid; rr = rr < 0 ? 0 : (rr > M - 1 ? M - 1 : rr); rt[ui * 256 + tid] = row_rstd(ws, E.slot, rr); }
.LBB0_484:
	v_add_u32_e32 v0, s22, v194
	v_mov_b32_e32 v3, 0x40ff
	v_med3_i32 v0, v0, 0, v3
	v_lshl_add_u64 v[4:5], s[10:11], 0, v[0:1]
	v_readlane_b32 s6, v252, 23
	v_lshlrev_b64 v[4:5], 6, v[4:5]
	v_readlane_b32 s7, v252, 24
	s_nop 1
	v_lshl_add_u64 v[16:17], s[6:7], 0, v[4:5]
	global_load_dwordx4 v[20:23], v[16:17], off
	global_load_dwordx4 v[24:27], v[16:17], off offset:32
	global_load_dwordx4 v[28:31], v[16:17], off offset:16
	s_nop 0
	global_load_dwordx4 v[32:35], v[16:17], off offset:48
	s_mov_b32 s6, 0x800000
	s_mov_b32 s101, 1

; __device__ __forceinline__ float row_rstd(const unsigned char* ws, int slot, int row) {
;     const f32x4* q = (const f32x4*)((const float*)(ws + WS_SS) + ((size_t)slot * M + row) * 16);
;     const f32x4 a = q[0], b = q[1], c = q[2], d = q[3];
; __global__ void __launch_bounds__(NTHR, 2) mega(Params p, int lo, int hi) {
;     ...
;                 Unit uu;
;                 for (int ui = 0; ui < 8 && S.next(ui, uu); ++ui) if (tid < 256) { int rr = ug ? 254 * uu.pm - 2 + tid : uu.pm * 256 + tid; rr = rr < 0 ? 0 : (rr > M - 1 ? M - 1 : rr); rt[ui * 256 + tid] = row_rstd(ws, E.slot, rr); }
.LBB0_497:
	v_add_u32_e32 v0, s23, v194
	v_mov_b32_e32 v3, 0x40ff
	v_med3_i32 v0, v0, 0, v3
	v_lshl_add_u64 v[4:5], s[10:11], 0, v[0:1]
	v_readlane_b32 s34, v252, 23
	v_lshlrev_b64 v[4:5], 6, v[4:5]
	v_readlane_b32 s35, v252, 24
	s_mov_b32 s14, 0x800000
	s_nop 0
	v_lshl_add_u64 v[16:17], s[34:35], 0, v[4:5]
	global_load_dwordx4 v[36:39], v[16:17], off
	global_load_dwordx4 v[40:43], v[16:17], off offset:32
	global_load_dwordx4 v[44:47], v[16:17], off offset:16
	s_nop 0
	global_load_dwordx4 v[48:51], v[16:17], off offset:48
	s_mov_b32 s101, 2

; __device__ __forceinline__ float row_rstd(const unsigned char* ws, int slot, int row) {
;     const f32x4* q = (const f32x4*)((const float*)(ws + WS_SS) + ((size_t)slot * M + row) * 16);
;     const f32x4 a = q[0], b = q[1], c = q[2], d = q[3];
; __global__ void __launch_bounds__(NTHR, 2) mega(Params p, int lo, int hi) {
;     ...
;                 Unit uu;
;                 for (int ui = 0; ui < 8 && S.next(ui, uu); ++ui) if (tid < 256) { int rr = ug ? 254 * uu.pm - 2 + tid : uu.pm * 256 + tid; rr = rr < 0 ? 0 : (rr > M - 1 ? M - 1 : rr); rt[ui * 256 + tid] = row_rstd(ws, E.slot, rr); }
.LBB0_510:
	v_add_u32_e32 v0, s23, v194
	v_mov_b32_e32 v3, 0x40ff
	v_med3_i32 v0, v0, 0, v3
	v_lshl_add_u64 v[4:5], s[10:11], 0, v[0:1]
	v_readlane_b32 s34, v252, 23
	v_lshlrev_b64 v[4:5], 6, v[4:5]
	v_readlane_b32 s35, v252, 24
	s_mov_b32 s14, 0x800000
	s_nop 0
	v_lshl_add_u64 v[16:17], s[34:35], 0, v[4:5]
	global_load_dwordx4 v[52:55], v[16:17], off
	global_load_dwordx4 v[56:59], v[16:17], off offset:32
	global_load_dwordx4 v[60:63], v[16:17], off offset:16
	s_nop 0
	global_load_dwordx4 v[64:67], v[16:17], off offset:48
	s_mov_b32 s101, 3

; __device__ __forceinline__ float row_rstd(const unsigned char* ws, int slot, int row) {
;     const f32x4* q = (const f32x4*)((const float*)(ws + WS_SS) + ((size_t)slot * M + row) * 16);
;     const f32x4 a = q[0], b = q[1], c = q[2], d = q[3];
; __global__ void __launch_bounds__(NTHR, 2) mega(Params p, int lo, int hi) {
;     ...
;                 Unit uu;
;                 for (int ui = 0; ui < 8 && S.next(ui, uu); ++ui) if (tid < 256) { int rr = ug ? 254 * uu.pm - 2 + tid : uu.pm * 256 + tid; rr = rr < 0 ? 0 : (rr > M - 1 ? M - 1 : rr); rt[ui * 256 + tid] = row_rstd(ws, E.slot, rr); }
.LBB0_523:
	v_add_u32_e32 v0, s23, v194
	v_mov_b32_e32 v3, 0x40ff
	v_med3_i32 v0, v0, 0, v3
	v_lshl_add_u64 v[4:5], s[10:11], 0, v[0:1]
	v_readlane_b32 s34, v252, 23
	v_lshlrev_b64 v[4:5], 6, v[4:5]
	v_readlane_b32 s35, v252, 24
	s_mov_b32 s14, 0x800000
	s_nop 0
	v_lshl_add_u64 v[16:17], s[34:35], 0, v[4:5]
	global_load_dwordx4 v[68:71], v[16:17], off
	global_load_dwordx4 v[72:75], v[16:17], off offset:32
	global_load_dwordx4 v[76:79], v[16:17], off offset:16
	s_nop 0
	global_load_dwordx4 v[80:83], v[16:17], off offset:48
	s_mov_b32 s101, 4

; __device__ __forceinline__ float row_rstd(const unsigned char* ws, int slot, int row) {
;     const f32x4* q = (const f32x4*)((const float*)(ws + WS_SS) + ((size_t)slot * M + row) * 16);
;     const f32x4 a = q[0], b = q[1], c = q[2], d = q[3];
; __global__ void __launch_bounds__(NTHR, 2) mega(Params p, int lo, int hi) {
;     ...
;                 Unit uu;
;                 for (int ui = 0; ui < 8 && S.next(ui, uu); ++ui) if (tid < 256) { int rr = ug ? 254 * uu.pm - 2 + tid : uu.pm * 256 + tid; rr = rr < 0 ? 0 : (rr > M - 1 ? M - 1 : rr); rt[ui * 256 + tid] = row_rstd(ws, E.slot, rr); }
.LBB0_536:
	v_add_u32_e32 v0, s23, v194
	v_mov_b32_e32 v3, 0x40ff
	v_med3_i32 v0, v0, 0, v3
	v_lshl_add_u64 v[4:5], s[10:11], 0, v[0:1]
	v_readlane_b32 s34, v252, 23
	v_lshlrev_b64 v[4:5], 6, v[4:5]
	v_readlane_b32 s35, v252, 24
	s_mov_b32 s14, 0x800000
	s_nop 0
	v_lshl_add_u64 v[16:17], s[34:35], 0, v[4:5]
	global_load_dwordx4 v[84:87], v[16:17], off
	global_load_dwordx4 v[88:91], v[16:17], off offset:32
	global_load_dwordx4 v[92:95], v[16:17], off offset:16
	s_nop 0
	global_load_dwordx4 v[96:99], v[16:17], off offset:48
	s_mov_b32 s101, 5

; __device__ __forceinline__ float row_rstd(const unsigned char* ws, int slot, int row) {
;     const f32x4* q = (const f32x4*)((const float*)(ws + WS_SS) + ((size_t)slot * M + row) * 16);
;     const f32x4 a = q[0], b = q[1], c = q[2], d = q[3];
; __global__ void __launch_bounds__(NTHR, 2) mega(Params p, int lo, int hi) {
;     ...
;                 Unit uu;
;                 for (int ui = 0; ui < 8 && S.next(ui, uu); ++ui) if (tid < 256) { int rr = ug ? 254 * uu.pm - 2 + tid : uu.pm * 256 + tid; rr = rr < 0 ? 0 : (rr > M - 1 ? M - 1 : rr); rt[ui * 256 + tid] = row_rstd(ws, E.slot, rr); }
.LBB0_549:
	v_add_u32_e32 v0, s23, v194
	v_mov_b32_e32 v3, 0x40ff
	v_med3_i32 v0, v0, 0, v3
	v_lshl_add_u64 v[4:5], s[10:11], 0, v[0:1]
	v_readlane_b32 s34, v252, 23
	v_lshlrev_b64 v[4:5], 6, v[4:5]
	v_readlane_b32 s35, v252, 24
	s_mov_b32 s14, 0x800000
	s_nop 0
	v_lshl_add_u64 v[16:17], s[34:35], 0, v[4:5]
	global_load_dwordx4 v[100:103], v[16:17], off
	global_load_dwordx4 v[104:107], v[16:17], off offset:32
	global_load_dwordx4 v[108:111], v[16:17], off offset:16
	s_nop 0
	global_load_dwordx4 v[112:115], v[16:17], off offset:48
	s_mov_b32 s101, 6

; __device__ __forceinline__ float row_rstd(const unsigned char* ws, int slot, int row) {
;     const f32x4* q = (const f32x4*)((const float*)(ws + WS_SS) + ((size_t)slot * M + row) * 16);
;     const f32x4 a = q[0], b = q[1], c = q[2], d = q[3];
; __global__ void __launch_bounds__(NTHR, 2) mega(Params p, int lo, int hi) {
;     ...
;                 Unit uu;
;                 for (int ui = 0; ui < 8 && S.next(ui, uu); ++ui) if (tid < 256) { int rr = ug ? 254 * uu.pm - 2 + tid : uu.pm * 256 + tid; rr = rr < 0 ? 0 : (rr > M - 1 ? M - 1 : rr); rt[ui * 256 + tid] = row_rstd(ws, E.slot, rr); }
.LBB0_562:
	v_add_u32_e32 v0, s23, v194
	v_mov_b32_e32 v3, 0x40ff
	v_med3_i32 v0, v0, 0, v3
	v_lshl_add_u64 v[4:5], s[10:11], 0, v[0:1]
	v_readlane_b32 s4, v252, 23
	v_lshlrev_b64 v[4:5], 6, v[4:5]
	v_readlane_b32 s5, v252, 24
	s_nop 1
	v_lshl_add_u64 v[16:17], s[4:5], 0, v[4:5]
	global_load_dwordx4 v[116:119], v[16:17], off
	global_load_dwordx4 v[120:123], v[16:17], off offset:32
	global_load_dwordx4 v[124:127], v[16:17], off offset:16
	s_nop 0
	global_load_dwordx4 v[128:131], v[16:17], off offset:48
	s_mov_b32 s4, 0x800000
	s_mov_b32 s101, 7

; __device__ __forceinline__ float row_rstd(const unsigned char* ws, int slot, int row) {
;     const f32x4* q = (const f32x4*)((const float*)(ws + WS_SS) + ((size_t)slot * M + row) * 16);
;     const f32x4 a = q[0], b = q[1], c = q[2], d = q[3];
; __global__ void __launch_bounds__(NTHR, 2) mega(Params p, int lo, int hi) {
;     ...
;                 Unit uu;
;                 for (int ui = 0; ui < 8 && S.next(ui, uu); ++ui) if (tid < 256) { int rr = ug ? 254 * uu.pm - 2 + tid : uu.pm * 256 + tid; rr = rr < 0 ? 0 : (rr > M - 1 ? M - 1 : rr); rt[ui * 256 + tid] = row_rstd(ws, E.slot, rr); }
.LBB0_574:
	v_add_u32_e32 v0, s6, v194
	v_mov_b32_e32 v3, 0x40ff
	v_med3_i32 v0, v0, 0, v3
	v_lshl_add_u64 v[4:5], s[10:11], 0, v[0:1]
	v_readlane_b32 s4, v252, 23
	v_lshlrev_b64 v[4:5], 6, v[4:5]
	v_readlane_b32 s5, v252, 24
	s_nop 1
	v_lshl_add_u64 v[16:17], s[4:5], 0, v[4:5]
	global_load_dwordx4 v[132:135], v[16:17], off
	global_load_dwordx4 v[136:139], v[16:17], off offset:32
	global_load_dwordx4 v[140:143], v[16:17], off offset:16
	s_nop 0
	global_load_dwordx4 v[144:147], v[16:17], off offset:48
	s_mov_b32 s4, 0x800000
	s_mov_b32 s101, 8

; __device__ __forceinline__ float row_rstd(const unsigned char* ws, int slot, int row) {
;     const f32x4* q = (const f32x4*)((const float*)(ws + WS_SS) + ((size_t)slot * M + row) * 16);
;     const f32x4 a = q[0], b = q[1], c = q[2], d = q[3];
;     const float ss = (((a.x + a.y) + (a.z + a.w)) + ((b.x + b.y) + (b.z + b.w))) + (((c.x + c.y) + (c.z + c.w)) + ((d.x + d.y) + (d.z + d.w)));
;     return rsqrtf(ss * (1.f / D) + 1e-6f);
; __global__ void __launch_bounds__(NTHR, 2) mega(Params p, int lo, int hi) {
;     ...
;                 for (int ui = 0; ui < 8 && S.next(ui, uu); ++ui) if (tid < 256) { int rr = ug ? 254 * uu.pm - 2 + tid : uu.pm * 256 + tid; rr = rr < 0 ? 0 : (rr > M - 1 ? M - 1 : rr); rt[ui * 256 + tid] = row_rstd(ws, E.slot, rr); }
;                 E.rtab = rt; E.ldsb = lds;
;                 __syncthreads();
.LBB0_578:
	s_cmp_eq_u32 s101, 0
	s_cbranch_scc1 .Lrstd_done
	v_cmp_gt_i32_e32 vcc, 0x100, v194
	s_and_saveexec_b64 s[0:1], vcc
	s_waitcnt vmcnt(0)
	v_add_f32_e32 v0, v20, v21
	v_add_f32_e32 v3, v22, v23
	v_add_f32_e32 v0, v0, v3
	v_add_f32_e32 v3, v28, v29
	v_add_f32_e32 v4, v30, v31
	v_add_f32_e32 v3, v3, v4
	v_add_f32_e32 v0, v0, v3
	v_add_f32_e32 v3, v24, v25
	v_add_f32_e32 v4, v26, v27
	v_add_f32_e32 v3, v3, v4
	v_add_f32_e32 v4, v32, v33
	v_add_f32_e32 v5, v34, v35
	v_add_f32_e32 v4, v4, v5
	v_add_f32_e32 v3, v3, v4
	v_add_f32_e32 v0, v0, v3
	v_fmamk_f32 v0, v0, 0x3a800000, v222
	v_mul_f32_e32 v3, 0x4b800000, v0
	v_cmp_gt_f32_e32 vcc, 0x800000, v0
	s_nop 1
	v_cndmask_b32_e32 v0, v0, v3, vcc
	v_rsq_f32_e32 v0, v0
	s_nop 0
	v_mul_f32_e32 v3, 0x45800000, v0
	v_cndmask_b32_e32 v0, v0, v3, vcc
	ds_write_b32 v2, v0
	s_cmp_lt_u32 s101, 2
	s_cbranch_scc1 .Lrstd_fin
	v_add_f32_e32 v0, v36, v37
	v_add_f32_e32 v3, v38, v39
	v_add_f32_e32 v0, v0, v3
	v_add_f32_e32 v3, v44, v45
	v_add_f32_e32 v4, v46, v47
	v_add_f32_e32 v3, v3, v4
	v_add_f32_e32 v0, v0, v3
	v_add_f32_e32 v3, v40, v41
	v_add_f32_e32 v4, v42, v43
	v_add_f32_e32 v3, v3, v4
	v_add_f32_e32 v4, v48, v49
	v_add_f32_e32 v5, v50, v51
	v_add_f32_e32 v4, v4, v5
	v_add_f32_e32 v3, v3, v4
	v_add_f32_e32 v0, v0, v3
	v_fmamk_f32 v0, v0, 0x3a800000, v222
	v_mul_f32_e32 v3, 0x4b800000, v0
	v_cmp_gt_f32_e32 vcc, 0x800000, v0
	s_nop 1
	v_cndmask_b32_e32 v0, v0, v3, vcc
	v_rsq_f32_e32 v0, v0
	s_nop 0
	v_mul_f32_e32 v3, 0x45800000, v0
	v_cndmask_b32_e32 v0, v0, v3, vcc
	ds_write_b32 v2, v0 offset:1024
	s_cmp_lt_u32 s101, 3
	s_cbranch_scc1 .Lrstd_fin
	v_add_f32_e32 v0, v52, v53
	v_add_f32_e32 v3, v54, v55
	v_add_f32_e32 v0, v0, v3
	v_add_f32_e32 v3, v60, v61
	v_add_f32_e32 v4, v62, v63
	v_add_f32_e32 v3, v3, v4
	v_add_f32_e32 v0, v0, v3
	v_add_f32_e32 v3, v56, v57
	v_add_f32_e32 v4, v58, v59
	v_add_f32_e32 v3, v3, v4
	v_add_f32_e32 v4, v64, v65
	v_add_f32_e32 v5, v66, v67
	v_add_f32_e32 v4, v4, v5
	v_add_f32_e32 v3, v3, v4
	v_add_f32_e32 v0, v0, v3
	v_fmamk_f32 v0, v0, 0x3a800000, v222
	v_mul_f32_e32 v3, 0x4b800000, v0
	v_cmp_gt_f32_e32 vcc, 0x800000, v0
	s_nop 1
	v_cndmask_b32_e32 v0, v0, v3, vcc
	v_rsq_f32_e32 v0, v0
	s_nop 0
	v_mul_f32_e32 v3, 0x45800000, v0
	v_cndmask_b32_e32 v0, v0, v3, vcc
	ds_write_b32 v2, v0 offset:2048
	s_cmp_lt_u32 s101, 4
	s_cbranch_scc1 .Lrstd_fin
	v_add_f32_e32 v0, v68, v69
	v_add_f32_e32 v3, v70, v71
	v_add_f32_e32 v0, v0, v3
	v_add_f32_e32 v3, v76, v77
	v_add_f32_e32 v4, v78, v79
	v_add_f32_e32 v3, v3, v4
	v_add_f32_e32 v0, v0, v3
	v_add_f32_e32 v3, v72, v73
	v_add_f32_e32 v4, v74, v75
	v_add_f32_e32 v3, v3, v4
	v_add_f32_e32 v4, v80, v81
	v_add_f32_e32 v5, v82, v83
	v_add_f32_e32 v4, v4, v5
	v_add_f32_e32 v3, v3, v4
	v_add_f32_e32 v0, v0, v3
	v_fmamk_f32 v0, v0, 0x3a800000, v222
	v_mul_f32_e32 v3, 0x4b800000, v0
	v_cmp_gt_f32_e32 vcc, 0x800000, v0
	s_nop 1
	v_cndmask_b32_e32 v0, v0, v3, vcc
	v_rsq_f32_e32 v0, v0
	s_nop 0
	v_mul_f32_e32 v3, 0x45800000, v0
	v_cndmask_b32_e32 v0, v0, v3, vcc
	ds_write_b32 v2, v0 offset:3072
	s_cmp_lt_u32 s101, 5
	s_cbranch_scc1 .Lrstd_fin
	v_add_f32_e32 v0, v84, v85
	v_add_f32_e32 v3, v86, v87
	v_add_f32_e32 v0, v0, v3
	v_add_f32_e32 v3, v92, v93
	v_add_f32_e32 v4, v94, v95
	v_add_f32_e32 v3, v3, v4
	v_add_f32_e32 v0, v0, v3
	v_add_f32_e32 v3, v88, v89
	v_add_f32_e32 v4, v90, v91
	v_add_f32_e32 v3, v3, v4
	v_add_f32_e32 v4, v96, v97
	v_add_f32_e32 v5, v98, v99
	v_add_f32_e32 v4, v4, v5
	v_add_f32_e32 v3, v3, v4
	v_add_f32_e32 v0, v0, v3
	v_fmamk_f32 v0, v0, 0x3a800000, v222
	v_mul_f32_e32 v3, 0x4b800000, v0
	v_cmp_gt_f32_e32 vcc, 0x800000, v0
	s_nop 1
	v_cndmask_b32_e32 v0, v0, v3, vcc
	v_rsq_f32_e32 v0, v0
	s_nop 0
	v_mul_f32_e32 v3, 0x45800000, v0
	v_cndmask_b32_e32 v0, v0, v3, vcc
	ds_write_b32 v2, v0 offset:4096
	s_cmp_lt_u32 s101, 6
	s_cbranch_scc1 .Lrstd_fin
	v_add_f32_e32 v0, v100, v101
	v_add_f32_e32 v3, v102, v103
	v_add_f32_e32 v0, v0, v3
	v_add_f32_e32 v3, v108, v109
	v_add_f32_e32 v4, v110, v111
	v_add_f32_e32 v3, v3, v4
	v_add_f32_e32 v0, v0, v3
	v_add_f32_e32 v3, v104, v105
	v_add_f32_e32 v4, v106, v107
	v_add_f32_e32 v3, v3, v4
	v_add_f32_e32 v4, v112, v113
	v_add_f32_e32 v5, v114, v115
	v_add_f32_e32 v4, v4, v5
	v_add_f32_e32 v3, v3, v4
	v_add_f32_e32 v0, v0, v3
	v_fmamk_f32 v0, v0, 0x3a800000, v222
	v_mul_f32_e32 v3, 0x4b800000, v0
	v_cmp_gt_f32_e32 vcc, 0x800000, v0
	s_nop 1
	v_cndmask_b32_e32 v0, v0, v3, vcc
	v_rsq_f32_e32 v0, v0
	s_nop 0
	v_mul_f32_e32 v3, 0x45800000, v0
	v_cndmask_b32_e32 v0, v0, v3, vcc
	ds_write_b32 v2, v0 offset:5120
	s_cmp_lt_u32 s101, 7
	s_cbranch_scc1 .Lrstd_fin
	v_add_f32_e32 v0, v116, v117
	v_add_f32_e32 v3, v118, v119
	v_add_f32_e32 v0, v0, v3
	v_add_f32_e32 v3, v124, v125
	v_add_f32_e32 v4, v126, v127
	v_add_f32_e32 v3, v3, v4
	v_add_f32_e32 v0, v0, v3
	v_add_f32_e32 v3, v120, v121
	v_add_f32_e32 v4, v122, v123
	v_add_f32_e32 v3, v3, v4
	v_add_f32_e32 v4, v128, v129
	v_add_f32_e32 v5, v130, v131
	v_add_f32_e32 v4, v4, v5
	v_add_f32_e32 v3, v3, v4
	v_add_f32_e32 v0, v0, v3
	v_fmamk_f32 v0, v0, 0x3a800000, v222
	v_mul_f32_e32 v3, 0x4b800000, v0
	v_cmp_gt_f32_e32 vcc, 0x800000, v0
	s_nop 1
	v_cndmask_b32_e32 v0, v0, v3, vcc
	v_rsq_f32_e32 v0, v0
	s_nop 0
	v_mul_f32_e32 v3, 0x45800000, v0
	v_cndmask_b32_e32 v0, v0, v3, vcc
	ds_write_b32 v2, v0 offset:6144
	s_cmp_lt_u32 s101, 8
	s_cbranch_scc1 .Lrstd_fin
	v_add_f32_e32 v0, v132, v133
	v_add_f32_e32 v3, v134, v135
	v_add_f32_e32 v0, v0, v3
	v_add_f32_e32 v3, v140, v141
	v_add_f32_e32 v4, v142, v143
	v_add_f32_e32 v3, v3, v4
	v_add_f32_e32 v0, v0, v3
	v_add_f32_e32 v3, v136, v137
	v_add_f32_e32 v4, v138, v139
	v_add_f32_e32 v3, v3, v4
	v_add_f32_e32 v4, v144, v145
	v_add_f32_e32 v5, v146, v147
	v_add_f32_e32 v4, v4, v5
	v_add_f32_e32 v3, v3, v4
	v_add_f32_e32 v0, v0, v3
	v_fmamk_f32 v0, v0, 0x3a800000, v222
	v_mul_f32_e32 v3, 0x4b800000, v0
	v_cmp_gt_f32_e32 vcc, 0x800000, v0
	s_nop 1
	v_cndmask_b32_e32 v0, v0, v3, vcc
	v_rsq_f32_e32 v0, v0
	s_nop 0
	v_mul_f32_e32 v3, 0x45800000, v0
	v_cndmask_b32_e32 v0, v0, v3, vcc
	ds_write_b32 v2, v0 offset:7168
.Lrstd_fin:
	s_or_b64 exec, exec, s[0:1]
.Lrstd_done:
	v_readlane_b32 s0, v254, 2
	s_waitcnt lgkmcnt(0)
	s_barrier
	v_writelane_b32 v255, s0, 34
